# P5 SSD units: wave work balanced - each wave runs the unit body twice over (row tile, head pair) items (row tiles 3-(w>>1) then w>>1, head pair by w&1) instead of one row tile x 4 heads, 10 inner iter
# speedup vs baseline: 1.0018x; 1.0009x over previous
.LBB0_917:
	s_or_b64 exec, exec, s[2:3]
	s_mov_b32 s99, s84
	s_mov_b32 s98, 0
	s_lshr_b32 s84, s99, 1
	s_sub_i32 s84, 3, s84
.Lp5_pass:
	s_lshl_b32 s0, s84, 5
	v_lshlrev_b32_e32 v2, 2, v227
	v_add_u32_e32 v11, s0, v98
	v_and_b32_e32 v10, 16, v2
	v_or_b32_e32 v2, v11, v231
	v_ashrrev_i32_e32 v3, 31, v2
	v_readlane_b32 s2, v253, 61
	v_lshlrev_b64 v[2:3], 9, v[2:3]
	v_readlane_b32 s3, v253, 62
	v_lshlrev_b32_e32 v114, 8, v5
	v_lshlrev_b32_e32 v8, 4, v232
	v_lshl_add_u64 v[2:3], s[2:3], 0, v[2:3]
	v_lshl_add_u64 v[2:3], v[2:3], 0, v[114:115]
	v_mov_b32_e32 v9, v115
	v_lshl_add_u64 v[2:3], v[2:3], 0, v[8:9]
	s_cmp_lg_u32 s98, 0
	s_cbranch_scc1 .Lp5_nobar
	s_waitcnt lgkmcnt(0)
	s_barrier
.Lp5_nobar:
	global_load_dwordx4 v[50:53], v[2:3], off
	global_load_dwordx4 v[54:57], v[2:3], off offset:32
	global_load_dwordx4 v[58:61], v[2:3], off offset:64
	global_load_dwordx4 v[62:65], v[2:3], off offset:96
	global_load_dwordx4 v[66:69], v[2:3], off offset:128
	global_load_dwordx4 v[70:73], v[2:3], off offset:160
	global_load_dwordx4 v[74:77], v[2:3], off offset:192
	global_load_dwordx4 v[78:81], v[2:3], off offset:224
	v_lshlrev_b32_e32 v2, 2, v1
	v_readlane_b32 s2, v253, 59
	v_and_b32_e32 v236, 4, v2
	v_or_b32_e32 v2, s0, v231
	v_readlane_b32 s3, v253, 60
	v_lshl_add_u32 v117, v2, 5, v225
	v_lshlrev_b32_e32 v6, 3, v232
	v_lshl_add_u64 v[2:3], s[2:3], 0, v[114:115]
	v_lshlrev_b32_e32 v114, 4, v231
	v_mov_b32_e32 v7, v115
	v_lshlrev_b32_e32 v101, 4, v4
	v_lshl_add_u64 v[4:5], s[66:67], 0, v[114:115]
	v_lshlrev_b32_e32 v100, 2, v232
	v_lshl_add_u64 v[104:105], v[4:5], 0, v[6:7]
	v_ashrrev_i32_e32 v6, 4, v11
	v_lshl_add_u64 v[102:103], v[2:3], 0, v[8:9]
	v_or_b32_e32 v2, v100, v11
	v_ashrrev_i32_e32 v7, 31, v6
	v_lshlrev_b64 v[108:109], 1, v[6:7]
	v_or_b32_e32 v6, 1, v2
	v_ashrrev_i32_e32 v7, 31, v6
	v_lshlrev_b64 v[112:113], 11, v[6:7]
	v_or_b32_e32 v6, 2, v2
	v_ashrrev_i32_e32 v7, 31, v6
	v_lshlrev_b64 v[118:119], 11, v[6:7]
	v_or_b32_e32 v6, 3, v2
	v_ashrrev_i32_e32 v7, 31, v6
	v_lshlrev_b64 v[120:121], 11, v[6:7]
	v_or_b32_e32 v6, 8, v2
	v_ashrrev_i32_e32 v7, 31, v6
	v_lshlrev_b64 v[122:123], 11, v[6:7]
	v_or_b32_e32 v6, 9, v2
	v_or_b32_e32 v3, 2, v100
	v_ashrrev_i32_e32 v7, 31, v6
	v_cmp_gt_u32_e64 s[8:9], v3, v231
	v_or_b32_e32 v3, 3, v100
	v_lshlrev_b64 v[124:125], 11, v[6:7]
	v_or_b32_e32 v6, 10, v2
	v_cmp_gt_u32_e64 s[10:11], v3, v231
	v_or_b32_e32 v3, 8, v100
	v_ashrrev_i32_e32 v7, 31, v6
	v_cmp_gt_u32_e64 s[12:13], v3, v231
	v_or_b32_e32 v3, 9, v100
	v_lshlrev_b64 v[126:127], 11, v[6:7]
	v_or_b32_e32 v6, 11, v2
	v_cmp_gt_u32_e64 s[14:15], v3, v231
	v_or_b32_e32 v3, 10, v100
	v_ashrrev_i32_e32 v7, 31, v6
	v_cmp_gt_u32_e64 s[16:17], v3, v231
	v_or_b32_e32 v3, 11, v100
	v_lshlrev_b64 v[128:129], 11, v[6:7]
	v_or_b32_e32 v6, 16, v2
	v_cmp_gt_u32_e64 s[18:19], v3, v231
	v_or_b32_e32 v3, 16, v100
	v_ashrrev_i32_e32 v7, 31, v6
	v_cmp_gt_u32_e64 s[20:21], v3, v231
	v_or_b32_e32 v3, 17, v100
	v_ashrrev_i32_e32 v8, 4, v6
	v_lshlrev_b64 v[132:133], 11, v[6:7]
	v_or_b32_e32 v6, 17, v2
	v_cmp_gt_u32_e64 s[22:23], v3, v231
	v_or_b32_e32 v3, 18, v100
	v_ashrrev_i32_e32 v7, 31, v6
	v_cmp_gt_u32_e64 s[24:25], v3, v231
	v_or_b32_e32 v3, 19, v100
	v_lshlrev_b64 v[134:135], 11, v[6:7]
	v_or_b32_e32 v6, 18, v2
	v_cmp_gt_u32_e64 s[26:27], v3, v231
	v_or_b32_e32 v3, 24, v100
	v_ashrrev_i32_e32 v7, 31, v6
	v_cmp_gt_u32_e64 s[28:29], v3, v231
	v_or_b32_e32 v3, 25, v100
	v_or_b32_e32 v4, 24, v2
	v_lshlrev_b64 v[136:137], 11, v[6:7]
	v_or_b32_e32 v6, 19, v2
	v_cmp_gt_u32_e64 s[30:31], v3, v231
	v_or_b32_e32 v3, 26, v100
	v_ashrrev_i32_e32 v5, 31, v4
	v_ashrrev_i32_e32 v7, 31, v6
	v_cmp_gt_u32_e64 s[34:35], v3, v231
	v_or_b32_e32 v3, 27, v100
	v_lshlrev_b64 v[138:139], 11, v[6:7]
	v_ashrrev_i32_e32 v6, 4, v4
	v_lshlrev_b64 v[142:143], 11, v[4:5]
	v_or_b32_e32 v4, 25, v2
	v_cmp_gt_u32_e64 s[36:37], v3, v231
	v_ashrrev_i32_e32 v3, 31, v2
	v_ashrrev_i32_e32 v5, 31, v4
	v_lshlrev_b32_e32 v13, 4, v116
	v_lshlrev_b64 v[110:111], 11, v[2:3]
	v_lshlrev_b64 v[144:145], 11, v[4:5]
	v_or_b32_e32 v4, 26, v2
	v_or_b32_e32 v2, 27, v2
	v_and_b32_e32 v114, 0x1f0, v13
	v_ashrrev_i32_e32 v5, 31, v4
	v_ashrrev_i32_e32 v3, 31, v2
	v_or_b32_e32 v12, s0, v100
	s_cmp_gt_i32 s84, -1
	v_lshl_add_u64 v[106:107], s[66:67], 0, v[114:115]
	v_ashrrev_i32_e32 v9, 31, v8
	v_ashrrev_i32_e32 v7, 31, v6
	v_lshlrev_b64 v[146:147], 11, v[4:5]
	v_lshlrev_b64 v[148:149], 11, v[2:3]
	v_and_b32_e32 v114, 0x3f0, v13
	v_lshl_or_b32 v2, v232, 7, v10
	v_mov_b32_e32 v198, 0
	s_cselect_b64 s[38:39], -1, 0
	v_lshlrev_b32_e32 v233, 5, v12
	v_cmp_gt_u32_e64 s[4:5], v100, v231
	v_cmp_ge_u32_e64 s[6:7], v100, v231
	v_lshlrev_b64 v[130:131], 1, v[8:9]
	v_lshlrev_b64 v[140:141], 1, v[6:7]
	v_or_b32_e32 v234, 3, v236
	v_lshl_add_u64 v[150:151], s[60:61], 0, v[114:115]
	v_lshl_add_u64 v[152:153], s[94:95], 0, v[110:111]
	v_lshl_add_u64 v[154:155], s[94:95], 0, v[112:113]
	v_lshl_add_u64 v[156:157], s[94:95], 0, v[118:119]
	v_lshl_add_u64 v[158:159], s[94:95], 0, v[120:121]
	v_lshl_add_u64 v[160:161], s[94:95], 0, v[122:123]
	v_lshl_add_u64 v[162:163], s[94:95], 0, v[124:125]
	v_lshl_add_u64 v[164:165], s[94:95], 0, v[126:127]
	v_lshl_add_u64 v[166:167], s[94:95], 0, v[128:129]
	v_lshl_add_u64 v[168:169], s[94:95], 0, v[132:133]
	v_lshl_add_u64 v[170:171], s[94:95], 0, v[134:135]
	v_lshl_add_u64 v[172:173], s[94:95], 0, v[136:137]
	v_lshl_add_u64 v[174:175], s[94:95], 0, v[138:139]
	v_lshl_add_u64 v[176:177], s[94:95], 0, v[142:143]
	v_lshl_add_u64 v[178:179], s[94:95], 0, v[144:145]
	v_lshl_add_u64 v[180:181], s[94:95], 0, v[146:147]
	v_lshl_add_u64 v[182:183], s[94:95], 0, v[148:149]
	s_add_i32 s1, s84, 1
	v_add_u32_e32 v235, v225, v2
	s_mov_b64 s[2:3], 0
	v_mov_b32_e32 v199, v198
	v_mov_b32_e32 v194, v198
	v_mov_b32_e32 v195, v198
	v_mov_b32_e32 v196, v198
	v_mov_b32_e32 v197, v198
	v_mov_b32_e32 v186, v198
	v_mov_b32_e32 v187, v198
	v_mov_b32_e32 v190, v198
	v_mov_b32_e32 v191, v198
	v_mov_b32_e32 v192, v198
	v_mov_b32_e32 v193, v198
	v_mov_b32_e32 v188, v198
	v_mov_b32_e32 v189, v198
	v_mov_b32_e32 v184, v198
	v_mov_b32_e32 v185, v198
	s_bitcmp1_b32 s99, 0
	s_cbranch_scc0 .Lp5_h01
	v_add_u32_e32 v236, 2, v236
	v_add_u32_e32 v235, 8, v235
.Lp5_h01:
	v_add_u32_e32 v234, 1, v236
	s_branch .LBB0_919

.LBB0_919:
	v_add_u32_e32 v200, v236, v99
	v_add_u32_e32 v2, v200, v101
	v_ashrrev_i32_e32 v3, 31, v2
	v_lshlrev_b64 v[2:3], 14, v[2:3]
	v_lshl_add_u64 v[22:23], v[150:151], 0, v[2:3]
	v_add_co_u32_e32 v202, vcc, s97, v22
	s_nop 1
	v_addc_co_u32_e32 v203, vcc, 0, v23, vcc
	v_add_co_u32_e32 v204, vcc, s82, v22
	s_nop 1
	v_addc_co_u32_e32 v205, vcc, 0, v23, vcc
	global_load_dwordx4 v[18:21], v[202:203], off offset:-4096
	global_load_dwordx4 v[22:25], v[204:205], off offset:-4096
	global_load_dwordx4 v[26:29], v[202:203], off offset:-3072
	global_load_dwordx4 v[30:33], v[204:205], off offset:-3072
	global_load_dwordx4 v[82:85], v[202:203], off offset:-2048
	global_load_dwordx4 v[86:89], v[204:205], off offset:-2048
	global_load_dwordx4 v[90:93], v[202:203], off offset:-1024
	global_load_dwordx4 v[94:97], v[204:205], off offset:-1024
	s_waitcnt vmcnt(7)
	v_mfma_f32_32x32x16_bf16 v[2:17], v[50:53], v[18:21], 0
	global_load_dwordx4 v[18:21], v[202:203], off
	s_waitcnt vmcnt(7)
	v_mfma_f32_32x32x16_bf16 v[34:49], v[50:53], v[22:25], 0
	global_load_dwordx4 v[22:25], v[204:205], off
	s_waitcnt vmcnt(7)
	v_mfma_f32_32x32x16_bf16 v[2:17], v[54:57], v[26:29], v[2:17]
	global_load_dwordx4 v[26:29], v[202:203], off offset:1024
	s_waitcnt vmcnt(7)
	v_mfma_f32_32x32x16_bf16 v[34:49], v[54:57], v[30:33], v[34:49]
	global_load_dwordx4 v[30:33], v[204:205], off offset:1024
	s_waitcnt vmcnt(7)
	v_mfma_f32_32x32x16_bf16 v[2:17], v[58:61], v[82:85], v[2:17]
	global_load_dwordx4 v[82:85], v[202:203], off offset:2048
	s_waitcnt vmcnt(7)
	v_mfma_f32_32x32x16_bf16 v[34:49], v[58:61], v[86:89], v[34:49]
	global_load_dwordx4 v[86:89], v[204:205], off offset:2048
	s_waitcnt vmcnt(7)
	v_mfma_f32_32x32x16_bf16 v[2:17], v[62:65], v[90:93], v[2:17]
	global_load_dwordx4 v[90:93], v[202:203], off offset:3072
	s_waitcnt vmcnt(7)
	v_mfma_f32_32x32x16_bf16 v[34:49], v[62:65], v[94:97], v[34:49]
	global_load_dwordx4 v[94:97], v[204:205], off offset:3072
	s_waitcnt vmcnt(7)
	v_mfma_f32_32x32x16_bf16 v[2:17], v[66:69], v[18:21], v[2:17]
	s_waitcnt vmcnt(6)
	v_mfma_f32_32x32x16_bf16 v[34:49], v[66:69], v[22:25], v[34:49]
	s_waitcnt vmcnt(5)
	v_mfma_f32_32x32x16_bf16 v[2:17], v[70:73], v[26:29], v[2:17]
	s_waitcnt vmcnt(4)
	v_mfma_f32_32x32x16_bf16 v[34:49], v[70:73], v[30:33], v[34:49]
	s_waitcnt vmcnt(3)
	v_mfma_f32_32x32x16_bf16 v[2:17], v[74:77], v[82:85], v[2:17]
	s_waitcnt vmcnt(2)
	v_mfma_f32_32x32x16_bf16 v[34:49], v[74:77], v[86:89], v[34:49]
	s_waitcnt vmcnt(1)
	v_mfma_f32_32x32x16_bf16 v[2:17], v[78:81], v[90:93], v[2:17]
	s_waitcnt vmcnt(0)
	v_mfma_f32_32x32x16_bf16 v[34:49], v[78:81], v[94:97], v[34:49]
	s_andn2_b64 vcc, exec, s[38:39]
	s_nop 0
	s_nop 0
	s_nop 0
	s_nop 0
	s_nop 0
	s_nop 0
	s_nop 0
	s_nop 0
	s_nop 0
	s_nop 0
	v_lshlrev_b32_e32 v18, 2, v236
	v_add3_u32 v20, v225, v18, v233
	ds_read2_b32 v[18:19], v20 offset1:8
	s_waitcnt lgkmcnt(0)
	v_mul_f32_e32 v18, 0x3fb8aa3b, v18
	v_exp_f32_e32 v82, v18
	v_mul_f32_e32 v18, 0x3fb8aa3b, v19
	v_exp_f32_e32 v83, v18
	ds_read2_b32 v[18:19], v20 offset0:16 offset1:24
	s_waitcnt lgkmcnt(0)
	v_mul_f32_e32 v18, 0x3fb8aa3b, v18
	v_exp_f32_e32 v84, v18
	v_mul_f32_e32 v18, 0x3fb8aa3b, v19
	v_exp_f32_e32 v85, v18
	ds_read2_b32 v[18:19], v20 offset0:64 offset1:72
	s_waitcnt lgkmcnt(0)
	v_mul_f32_e32 v18, 0x3fb8aa3b, v18
	v_exp_f32_e32 v86, v18
	v_mul_f32_e32 v18, 0x3fb8aa3b, v19
	v_exp_f32_e32 v87, v18
	ds_read2_b32 v[18:19], v20 offset0:80 offset1:88
	v_pk_mul_f32 v[22:23], v[6:7], v[86:87]
	v_pk_mul_f32 v[6:7], v[38:39], v[86:87]
	s_waitcnt lgkmcnt(0)
	v_mul_f32_e32 v18, 0x3fb8aa3b, v18
	v_exp_f32_e32 v88, v18
	v_mul_f32_e32 v18, 0x3fb8aa3b, v19
	v_exp_f32_e32 v89, v18
	ds_read2_b32 v[18:19], v20 offset0:128 offset1:136
	v_pk_mul_f32 v[24:25], v[8:9], v[88:89]
	v_pk_mul_f32 v[8:9], v[40:41], v[88:89]
	s_waitcnt lgkmcnt(0)
	v_mul_f32_e32 v18, 0x3fb8aa3b, v18
	v_exp_f32_e32 v90, v18
	v_mul_f32_e32 v18, 0x3fb8aa3b, v19
	v_exp_f32_e32 v91, v18
	ds_read2_b32 v[18:19], v20 offset0:144 offset1:152
	v_pk_mul_f32 v[26:27], v[10:11], v[90:91]
	v_pk_mul_f32 v[10:11], v[42:43], v[90:91]
	s_waitcnt lgkmcnt(0)
	v_mul_f32_e32 v18, 0x3fb8aa3b, v18
	v_exp_f32_e32 v92, v18
	v_mul_f32_e32 v18, 0x3fb8aa3b, v19
	v_exp_f32_e32 v93, v18
	ds_read2_b32 v[18:19], v20 offset0:192 offset1:200
	v_pk_mul_f32 v[28:29], v[12:13], v[92:93]
	v_pk_mul_f32 v[12:13], v[44:45], v[92:93]
	s_waitcnt lgkmcnt(0)
	v_mul_f32_e32 v18, 0x3fb8aa3b, v18
	v_exp_f32_e32 v94, v18
	v_mul_f32_e32 v18, 0x3fb8aa3b, v19
	v_exp_f32_e32 v95, v18
	ds_read2_b32 v[18:19], v20 offset0:208 offset1:216
	v_pk_mul_f32 v[20:21], v[4:5], v[84:85]
	v_pk_mul_f32 v[4:5], v[36:37], v[84:85]
	v_pk_mul_f32 v[30:31], v[14:15], v[94:95]
	v_pk_mul_f32 v[14:15], v[46:47], v[94:95]
	s_waitcnt lgkmcnt(0)
	v_mul_f32_e32 v18, 0x3fb8aa3b, v18
	v_exp_f32_e32 v96, v18
	v_mul_f32_e32 v18, 0x3fb8aa3b, v19
	v_exp_f32_e32 v97, v18
	v_pk_mul_f32 v[18:19], v[2:3], v[82:83]
	v_pk_mul_f32 v[2:3], v[34:35], v[82:83]
	v_pk_mul_f32 v[32:33], v[16:17], v[96:97]
	v_pk_mul_f32 v[16:17], v[48:49], v[96:97]
	s_cbranch_vccnz .LBB0_918
	v_lshl_add_u32 v34, v236, 2, v117
	ds_read_b32 v201, v34
	v_lshlrev_b32_e32 v114, 1, v200
	v_lshlrev_b64 v[202:203], 20, v[114:115]
	v_or_b32_e32 v114, 1, v114
	v_lshlrev_b64 v[204:205], 20, v[114:115]
	s_mov_b32 s86, 0
	v_mov_b32_e32 v206, v98
	v_mov_b32_e32 v207, v235

.Lp5_passend:
	s_waitcnt lgkmcnt(0)
	s_or_b64 exec, exec, s[72:73]
	s_cmp_lg_u32 s98, 0
	s_cbranch_scc1 .Lp5_done
	s_mov_b32 s98, 1
	s_lshr_b32 s84, s99, 1
	v_bfe_u32 v5, v1, 1, 1
	v_ashrrev_i32_e32 v4, 2, v1
	v_lshlrev_b32_e32 v99, 3, v5
	s_branch .Lp5_pass
.Lp5_done:
	s_mov_b32 s84, s99
.LBB0_954:
	s_or_b64 exec, exec, s[72:73]
	s_movk_i32 s0, 0x1ff
	v_cmp_lt_i32_e32 vcc, s0, v1
	s_and_saveexec_b64 s[36:37], vcc
	s_cbranch_execz .LBB0_900
	v_add_u32_e32 v2, 0xfffffe00, v1
	v_lshrrev_b32_e32 v3, 9, v2
	v_xor_b32_e32 v3, v3, v1
	v_lshlrev_b32_e32 v3, 1, v3
	v_lshrrev_b32_e32 v4, 3, v2
	v_and_b32_e32 v3, 2, v3
	s_ashr_i32 s0, s85, 7
	v_lshlrev_b32_e32 v2, 7, v4
	v_add_u32_e32 v74, s0, v3
	v_lshl_add_u32 v117, v74, 5, v2
	v_or_b32_e32 v2, v117, v231
	v_ashrrev_i32_e32 v3, 31, v2
	v_readlane_b32 s0, v253, 63
	v_bfe_u32 v75, v1, 1, 2
	v_lshlrev_b64 v[2:3], 10, v[2:3]
	v_readlane_b32 s1, v254, 0
	v_lshlrev_b32_e32 v118, 8, v75
	v_mov_b32_e32 v119, v115
	v_lshl_add_u64 v[2:3], s[0:1], 0, v[2:3]
	v_lshl_add_u64 v[2:3], v[2:3], 0, v[118:119]
	v_lshlrev_b32_e32 v120, 4, v232
	v_mov_b32_e32 v121, v115
	v_lshl_add_u64 v[72:73], v[2:3], 0, v[120:121]
	global_load_dwordx4 v[82:85], v[72:73], off
	v_lshl_or_b32 v114, v4, 2, v75
	v_lshlrev_b32_e32 v4, 4, v116
	s_bfe_u32 s85, s85, 0x10006
	v_lshlrev_b64 v[2:3], 16, v[114:115]
	v_and_b32_e32 v4, 0x3f0, v4
	v_lshl_add_u64 v[2:3], s[68:69], 0, v[2:3]
	v_lshl_or_b32 v114, s85, 15, v4
	v_lshl_add_u64 v[80:81], v[2:3], 0, v[114:115]
	s_waitcnt lgkmcnt(0)
	v_lshlrev_b32_e32 v119, 2, v232
	s_mov_b64 s[0:1], 0x1000
	v_lshl_add_u64 v[200:201], v[80:81], 0, s[0:1]
	s_mov_b64 s[0:1], 0x3000
	v_lshl_add_u64 v[202:203], v[80:81], 0, s[0:1]
	s_mov_b64 s[0:1], 0x5000
	v_lshl_add_u64 v[204:205], v[80:81], 0, s[0:1]
	s_mov_b64 s[0:1], 0x7000
	v_lshl_add_u64 v[206:207], v[80:81], 0, s[0:1]
	global_load_dwordx4 v[86:89], v[72:73], off offset:32
	global_load_dwordx4 v[90:93], v[72:73], off offset:64
	global_load_dwordx4 v[94:97], v[72:73], off offset:96
	global_load_dwordx4 v[98:101], v[72:73], off offset:128
	global_load_dwordx4 v[102:105], v[72:73], off offset:160
	global_load_dwordx4 v[106:109], v[72:73], off offset:192
	global_load_dwordx4 v[110:113], v[72:73], off offset:224
	global_load_dwordx4 v[134:137], v[200:201], off offset:-4096
	global_load_dwordx4 v[138:141], v[202:203], off offset:-4096
	global_load_dwordx4 v[142:145], v[204:205], off offset:-4096
	global_load_dwordx4 v[146:149], v[206:207], off offset:-4096
	global_load_dwordx4 v[150:153], v[200:201], off offset:-3072
	global_load_dwordx4 v[154:157], v[202:203], off offset:-3072
	global_load_dwordx4 v[158:161], v[204:205], off offset:-3072
	global_load_dwordx4 v[162:165], v[206:207], off offset:-3072
	global_load_dwordx4 v[166:169], v[200:201], off offset:-2048
	global_load_dwordx4 v[170:173], v[202:203], off offset:-2048
	global_load_dwordx4 v[174:177], v[204:205], off offset:-2048
	global_load_dwordx4 v[178:181], v[206:207], off offset:-2048
	s_waitcnt vmcnt(11)
	v_mfma_f32_32x32x16_bf16 v[50:65], v[82:85], v[134:137], 0
	global_load_dwordx4 v[134:137], v[200:201], off offset:-1024
	s_waitcnt vmcnt(11)
	v_mfma_f32_32x32x16_bf16 v[34:49], v[82:85], v[138:141], 0
	global_load_dwordx4 v[138:141], v[202:203], off offset:-1024
	s_waitcnt vmcnt(11)
	v_mfma_f32_32x32x16_bf16 v[18:33], v[82:85], v[142:145], 0
	global_load_dwordx4 v[142:145], v[204:205], off offset:-1024
	s_waitcnt vmcnt(11)
	v_mfma_f32_32x32x16_bf16 v[2:17], v[82:85], v[146:149], 0
	global_load_dwordx4 v[146:149], v[206:207], off offset:-1024
	s_waitcnt vmcnt(11)
	v_mfma_f32_32x32x16_bf16 v[50:65], v[86:89], v[150:153], v[50:65]
	global_load_dwordx4 v[150:153], v[200:201], off
	s_waitcnt vmcnt(11)
	v_mfma_f32_32x32x16_bf16 v[34:49], v[86:89], v[154:157], v[34:49]
	global_load_dwordx4 v[154:157], v[202:203], off
	s_waitcnt vmcnt(11)
	v_mfma_f32_32x32x16_bf16 v[18:33], v[86:89], v[158:161], v[18:33]
	global_load_dwordx4 v[158:161], v[204:205], off
	s_waitcnt vmcnt(11)
	v_mfma_f32_32x32x16_bf16 v[2:17], v[86:89], v[162:165], v[2:17]
	global_load_dwordx4 v[162:165], v[206:207], off
	s_waitcnt vmcnt(11)
	v_mfma_f32_32x32x16_bf16 v[50:65], v[90:93], v[166:169], v[50:65]
	global_load_dwordx4 v[166:169], v[200:201], off offset:1024
	s_waitcnt vmcnt(11)
	v_mfma_f32_32x32x16_bf16 v[34:49], v[90:93], v[170:173], v[34:49]
	global_load_dwordx4 v[170:173], v[202:203], off offset:1024
	s_waitcnt vmcnt(11)
	v_mfma_f32_32x32x16_bf16 v[18:33], v[90:93], v[174:177], v[18:33]
	global_load_dwordx4 v[174:177], v[204:205], off offset:1024
	s_waitcnt vmcnt(11)
	v_mfma_f32_32x32x16_bf16 v[2:17], v[90:93], v[178:181], v[2:17]
	global_load_dwordx4 v[178:181], v[206:207], off offset:1024
	s_waitcnt vmcnt(11)
	v_mfma_f32_32x32x16_bf16 v[50:65], v[94:97], v[134:137], v[50:65]
	global_load_dwordx4 v[134:137], v[200:201], off offset:2048
	s_waitcnt vmcnt(11)
	v_mfma_f32_32x32x16_bf16 v[34:49], v[94:97], v[138:141], v[34:49]
	global_load_dwordx4 v[138:141], v[202:203], off offset:2048
	s_waitcnt vmcnt(11)
	v_mfma_f32_32x32x16_bf16 v[18:33], v[94:97], v[142:145], v[18:33]
	global_load_dwordx4 v[142:145], v[204:205], off offset:2048
	s_waitcnt vmcnt(11)
	v_mfma_f32_32x32x16_bf16 v[2:17], v[94:97], v[146:149], v[2:17]
	global_load_dwordx4 v[146:149], v[206:207], off offset:2048
	s_waitcnt vmcnt(11)
	v_mfma_f32_32x32x16_bf16 v[50:65], v[98:101], v[150:153], v[50:65]
	global_load_dwordx4 v[150:153], v[200:201], off offset:3072
	s_waitcnt vmcnt(11)
	v_mfma_f32_32x32x16_bf16 v[34:49], v[98:101], v[154:157], v[34:49]
	global_load_dwordx4 v[154:157], v[202:203], off offset:3072
	s_waitcnt vmcnt(11)
	v_mfma_f32_32x32x16_bf16 v[18:33], v[98:101], v[158:161], v[18:33]
	global_load_dwordx4 v[158:161], v[204:205], off offset:3072
	s_waitcnt vmcnt(11)
	v_mfma_f32_32x32x16_bf16 v[2:17], v[98:101], v[162:165], v[2:17]
	global_load_dwordx4 v[162:165], v[206:207], off offset:3072
	s_waitcnt vmcnt(11)
	v_mfma_f32_32x32x16_bf16 v[50:65], v[102:105], v[166:169], v[50:65]
	s_waitcnt vmcnt(10)
	v_mfma_f32_32x32x16_bf16 v[34:49], v[102:105], v[170:173], v[34:49]
	s_waitcnt vmcnt(9)
	v_mfma_f32_32x32x16_bf16 v[18:33], v[102:105], v[174:177], v[18:33]
	s_waitcnt vmcnt(8)
	v_mfma_f32_32x32x16_bf16 v[2:17], v[102:105], v[178:181], v[2:17]
	s_waitcnt vmcnt(7)
	v_mfma_f32_32x32x16_bf16 v[50:65], v[106:109], v[134:137], v[50:65]
	s_waitcnt vmcnt(6)
	v_mfma_f32_32x32x16_bf16 v[34:49], v[106:109], v[138:141], v[34:49]
	s_waitcnt vmcnt(5)
	v_mfma_f32_32x32x16_bf16 v[18:33], v[106:109], v[142:145], v[18:33]
	s_waitcnt vmcnt(4)
	v_mfma_f32_32x32x16_bf16 v[2:17], v[106:109], v[146:149], v[2:17]
	v_cmp_lt_i32_e32 vcc, -1, v74
	s_waitcnt vmcnt(3)
	v_mfma_f32_32x32x16_bf16 v[50:65], v[110:113], v[150:153], v[50:65]
	s_waitcnt vmcnt(2)
	v_mfma_f32_32x32x16_bf16 v[34:49], v[110:113], v[154:157], v[34:49]
	s_waitcnt vmcnt(1)
	v_mfma_f32_32x32x16_bf16 v[18:33], v[110:113], v[158:161], v[18:33]
	s_waitcnt vmcnt(0)
	v_mfma_f32_32x32x16_bf16 v[2:17], v[110:113], v[162:165], v[2:17]
	s_and_saveexec_b64 s[2:3], vcc
	s_cbranch_execz .LBB0_961
	s_nop 0
	s_nop 0
	s_nop 0
	s_nop 0
	s_nop 0
	s_nop 0
	s_nop 0
	s_nop 0
	s_nop 0
	s_nop 0
	s_nop 0
	s_nop 0
	v_lshlrev_b32_e32 v67, 4, v228
	v_lshlrev_b32_e32 v66, 7, v75
	v_and_b32_e32 v70, 0xffffff80, v67
	v_lshlrev_b32_e32 v67, 13, v1
	v_readlane_b32 s0, v254, 1
	v_lshlrev_b32_e32 v114, 3, v232
	v_and_b32_e32 v72, 0xc000, v67
	v_lshlrev_b32_e32 v66, 1, v66
	v_mov_b32_e32 v67, v115
	v_readlane_b32 s1, v254, 2
	v_lshlrev_b32_e32 v68, 1, v114
	v_mov_b32_e32 v69, v115
	v_lshl_add_u64 v[66:67], s[0:1], 0, v[66:67]
	v_readlane_b32 s0, v254, 3
	v_lshl_add_u64 v[122:123], v[66:67], 0, v[68:69]
	v_lshlrev_b32_e32 v66, 4, v231
	v_mov_b32_e32 v67, v115
	v_readlane_b32 s1, v254, 4
	v_lshrrev_b32_e32 v71, 3, v70
	s_lshl_b32 s34, s85, 13
	v_lshl_add_u64 v[66:67], s[0:1], 0, v[66:67]
	v_lshl_add_u64 v[124:125], v[66:67], 0, v[114:115]
	v_or_b32_e32 v66, 2, v119
	v_cmp_gt_u32_e64 s[6:7], v66, v231
	v_or_b32_e32 v66, 3, v119
	v_cmp_gt_u32_e64 s[8:9], v66, v231
	v_or_b32_e32 v66, 8, v119
	v_cmp_gt_u32_e64 s[10:11], v66, v231
	v_or_b32_e32 v66, 9, v119
	v_cmp_gt_u32_e64 s[12:13], v66, v231
	v_or_b32_e32 v66, 10, v119
	v_cmp_gt_u32_e64 s[14:15], v66, v231
	v_or_b32_e32 v66, 11, v119
	v_cmp_gt_u32_e64 s[16:17], v66, v231
	v_or_b32_e32 v66, 16, v119
	v_cmp_gt_u32_e64 s[18:19], v66, v231
	v_or_b32_e32 v66, 17, v119
	v_cmp_gt_u32_e64 s[20:21], v66, v231
	v_or_b32_e32 v66, 18, v119
	v_cmp_gt_u32_e64 s[22:23], v66, v231
	v_or_b32_e32 v66, 19, v119
	v_cmp_gt_u32_e64 s[24:25], v66, v231
	v_or_b32_e32 v66, 24, v119
	v_cmp_gt_u32_e64 s[0:1], v66, v231
	v_or_b32_e32 v66, 25, v119
	v_cmp_gt_u32_e64 s[26:27], v66, v231
	v_or_b32_e32 v66, 26, v119
	v_cmp_gt_u32_e64 s[28:29], v66, v231
	v_or_b32_e32 v66, 27, v119
	v_cmp_gt_u32_e64 s[30:31], v66, v231
	v_add3_u32 v66, v71, v72, s34
	v_cmp_gt_u32_e32 vcc, v119, v231
	v_cmp_lt_u32_e64 s[4:5], v119, v231
	v_sub_u32_e32 v121, 0, v74
	v_add_u32_e32 v126, 0x1803, v66
	v_or_b32_e32 v114, v70, v231
	s_mov_b64 s[38:39], 0
	s_branch .LBB0_958
